# fast path v2: tile-A exps interleaved into tile-B QK MFMA shadow
# baseline (speedup 1.0000x reference)
; #define MFMA32(a, b, c) __builtin_amdgcn_mfma_f32_32x32x16_bf16((a), (b), (c), 0, 0, 0)
; DI int crow(int r, int h) { return (r & 3) + 8 * (r >> 2) + 4 * h; }
; DI void attn_item(const Params& p, int g, int seq, int hd, int qt, int m, char* smem, int split_j, int sub) {
;     ...
;   auto compute = [&](int st, int buf) __attribute__((always_inline)) {
;     const int k0 = (tbase + st) * 32, h = h_, l31 = l31_;
;     const bf16_t* Kb = Ks + buf * 32 * 72; const bf16_t* Vb = Vs + buf * 128 * 40;
;     const int rmin = k0 - (qw0 + 31), rmax = k0 + 31 - qw0;
;     const bool farL = rmax <= -128, farR = rmin >= 128;
;     if (!farL && region == 0) { rescale(__builtin_amdgcn_exp2f(cneg)); region = 1; }
;     if (farR && region == 1) { rescale(__builtin_amdgcn_exp2f(-cpos)); region = 2; }
;     bf16x8 kf[4], vf[2][4];
; #pragma unroll
;     for (int s = 0; s < 4; ++s) kf[s] = *(const bf16x8*)(Kb + l31 * 72 + s * 16 + h * 8);
; #pragma unroll
;     for (int s2 = 0; s2 < 2; ++s2)
; #pragma unroll
;       for (int dt = 0; dt < 4; ++dt) vf[s2][dt] = *(const bf16x8*)(Vb + (dt * 32 + l31) * 40 + s2 * 16 + h * 8);
;     __builtin_amdgcn_sched_barrier(0);
;     f32x16 X;
; #pragma unroll
;     for (int r = 0; r < 16; ++r) X[r] = 0.f;
; #pragma unroll
;     for (int s = 0; s < 4; ++s) X = MFMA32(kf[s], qf[s], X);
;     if (farL || farR) {
; #pragma unroll
;       for (int r = 0; r < 16; ++r) X[r] = __builtin_amdgcn_exp2f(X[r]);
;     } else {
;       const int rel0 = k0 - (qw0 + l31) + 128;
; #pragma unroll
;       for (int r = 0; r < 16; ++r) { int idx = rel0 + crow(r, h); idx = idx < 0 ? 0 : (idx > 256 ? 256 : idx); X[r] = __builtin_amdgcn_exp2f(X[r] + tab[idx]); }
;     }
;     bf16x8 pf[2];
; #pragma unroll
;     for (int s2 = 0; s2 < 2; ++s2) {
;       u32x4 w; w.x = pk_bf16(X[8 * s2], X[8 * s2 + 1]); w.y = pk_bf16(X[8 * s2 + 2], X[8 * s2 + 3]); w.z = pk_bf16(X[8 * s2 + 4], X[8 * s2 + 5]); w.w = pk_bf16(X[8 * s2 + 6], X[8 * s2 + 7]);
;       ls2 += (f32x2){X[8 * s2], X[8 * s2 + 1]}; ls2 += (f32x2){X[8 * s2 + 2], X[8 * s2 + 3]};
;       ls2 += (f32x2){X[8 * s2 + 4], X[8 * s2 + 5]}; ls2 += (f32x2){X[8 * s2 + 6], X[8 * s2 + 7]};
;       pf[s2] = __builtin_bit_cast(bf16x8, w);
;     }
; #pragma unroll
;     for (int s2 = 0; s2 < 2; ++s2)
; #pragma unroll
;       for (int dt = 0; dt < 4; ++dt) O[dt] = MFMA32(pf[s2], vf[s2][dt], O[dt]);
;   };
.Lat2_fast:
	s_add_i32 s10, s6, -3
	s_and_b32 s16, s10, 2
	s_mul_i32 s10, s16, 0x1200
	s_mul_i32 s18, s16, 0x2800
	v_add_u32_e32 v192, s10, v191
	v_add_u32_e32 v244, s18, v196
	ds_read_b128 v[64:67], v192
	ds_read_b128 v[80:83], v192 offset:32
	ds_read_b128 v[84:87], v192 offset:64
	ds_read_b128 v[88:91], v192 offset:96
	ds_read_b128 v[220:223], v192 offset:4608
	ds_read_b128 v[224:227], v192 offset:4640
	ds_read_b128 v[236:239], v192 offset:4672
	ds_read_b128 v[240:243], v192 offset:4704
	ds_read_b128 v[156:159], v244 offset:18432
	ds_read_b128 v[160:163], v244 offset:20992
	ds_read_b128 v[164:167], v244 offset:23552
	ds_read_b128 v[152:155], v244 offset:26112
	s_waitcnt lgkmcnt(11)
	v_mfma_f32_32x32x16_bf16 v[64:79], v[64:67], v[104:107], 0
	s_waitcnt lgkmcnt(10)
	v_mfma_f32_32x32x16_bf16 v[64:79], v[80:83], v[108:111], v[64:79]
	s_waitcnt lgkmcnt(9)
	v_mfma_f32_32x32x16_bf16 v[64:79], v[84:87], v[112:115], v[64:79]
	s_waitcnt lgkmcnt(8)
	v_mfma_f32_32x32x16_bf16 v[64:79], v[88:91], v[116:119], v[64:79]
	ds_read_b128 v[148:151], v244 offset:18464
	ds_read_b128 v[144:147], v244 offset:21024
	ds_read_b128 v[136:139], v244 offset:23584
	ds_read_b128 v[140:143], v244 offset:26144
	s_waitcnt lgkmcnt(11)
	v_mfma_f32_32x32x16_bf16 v[80:95], v[220:223], v[104:107], 0
	s_waitcnt lgkmcnt(10)
	v_mfma_f32_32x32x16_bf16 v[80:95], v[224:227], v[108:111], v[80:95]
	v_exp_f32_e32 v64, v64
	v_exp_f32_e32 v65, v65
	v_exp_f32_e32 v66, v66
	v_exp_f32_e32 v67, v67
	v_exp_f32_e32 v68, v68
	v_exp_f32_e32 v69, v69
	s_waitcnt lgkmcnt(9)
	v_mfma_f32_32x32x16_bf16 v[80:95], v[236:239], v[112:115], v[80:95]
	v_exp_f32_e32 v70, v70
	v_exp_f32_e32 v71, v71
	v_exp_f32_e32 v72, v72
	v_exp_f32_e32 v73, v73
	v_exp_f32_e32 v74, v74
	v_exp_f32_e32 v75, v75
	s_waitcnt lgkmcnt(8)
	v_mfma_f32_32x32x16_bf16 v[80:95], v[240:243], v[116:119], v[80:95]
	v_exp_f32_e32 v76, v76
	v_exp_f32_e32 v77, v77
	v_exp_f32_e32 v78, v78
	v_exp_f32_e32 v79, v79
	v_pk_add_f32 v[246:247], v[66:67], v[70:71]
	v_pk_add_f32 v[186:187], v[186:187], v[64:65]
	v_pk_add_f32 v[246:247], v[246:247], v[74:75]
	v_pk_add_f32 v[186:187], v[186:187], v[68:69]
	v_pk_add_f32 v[246:247], v[246:247], v[78:79]
	v_pk_add_f32 v[186:187], v[186:187], v[72:73]
	v_pk_add_f32 v[186:187], v[186:187], v[76:77]
	v_pk_add_f32 v[186:187], v[186:187], v[246:247]
	v_cvt_pk_bf16_f32 v64, v64, v65
	v_cvt_pk_bf16_f32 v65, v66, v67
	v_cvt_pk_bf16_f32 v66, v68, v69
	v_cvt_pk_bf16_f32 v67, v70, v71
	v_cvt_pk_bf16_f32 v68, v72, v73
	v_cvt_pk_bf16_f32 v69, v74, v75
	v_cvt_pk_bf16_f32 v70, v76, v77
	v_cvt_pk_bf16_f32 v71, v78, v79
	s_waitcnt lgkmcnt(7)
	v_mfma_f32_32x32x16_bf16 v[48:63], v[64:67], v[156:159], v[48:63]
	ds_read_b128 v[156:159], v244 offset:28672
	v_exp_f32_e32 v80, v80
	v_exp_f32_e32 v81, v81
	v_exp_f32_e32 v82, v82
	s_waitcnt lgkmcnt(7)
	v_mfma_f32_32x32x16_bf16 v[32:47], v[64:67], v[160:163], v[32:47]
	ds_read_b128 v[160:163], v244 offset:31232
	v_exp_f32_e32 v83, v83
	v_exp_f32_e32 v84, v84
	v_exp_f32_e32 v85, v85
	s_waitcnt lgkmcnt(7)
	v_mfma_f32_32x32x16_bf16 v[16:31], v[64:67], v[164:167], v[16:31]
	ds_read_b128 v[164:167], v244 offset:33792
	v_exp_f32_e32 v86, v86
	v_exp_f32_e32 v87, v87
	v_exp_f32_e32 v88, v88
	s_waitcnt lgkmcnt(7)
	v_mfma_f32_32x32x16_bf16 v[0:15], v[64:67], v[152:155], v[0:15]
	ds_read_b128 v[152:155], v244 offset:36352
	v_exp_f32_e32 v89, v89
	v_exp_f32_e32 v90, v90
	v_exp_f32_e32 v91, v91
	s_waitcnt lgkmcnt(7)
	v_mfma_f32_32x32x16_bf16 v[48:63], v[68:71], v[148:151], v[48:63]
	ds_read_b128 v[148:151], v244 offset:28704
	v_exp_f32_e32 v92, v92
	v_exp_f32_e32 v93, v93
	v_exp_f32_e32 v94, v94
	v_exp_f32_e32 v95, v95
	s_waitcnt lgkmcnt(7)
	v_mfma_f32_32x32x16_bf16 v[32:47], v[68:71], v[144:147], v[32:47]
	ds_read_b128 v[144:147], v244 offset:31264
	v_pk_add_f32 v[246:247], v[82:83], v[86:87]
	v_pk_add_f32 v[186:187], v[186:187], v[80:81]
	v_pk_add_f32 v[246:247], v[246:247], v[90:91]
	v_pk_add_f32 v[186:187], v[186:187], v[84:85]
	s_waitcnt lgkmcnt(7)
	v_mfma_f32_32x32x16_bf16 v[16:31], v[68:71], v[136:139], v[16:31]
	ds_read_b128 v[136:139], v244 offset:33824
	v_pk_add_f32 v[246:247], v[246:247], v[94:95]
	v_pk_add_f32 v[186:187], v[186:187], v[88:89]
	v_pk_add_f32 v[186:187], v[186:187], v[92:93]
	v_pk_add_f32 v[186:187], v[186:187], v[246:247]
	s_waitcnt lgkmcnt(7)
	v_mfma_f32_32x32x16_bf16 v[0:15], v[68:71], v[140:143], v[0:15]
	ds_read_b128 v[140:143], v244 offset:36384
	v_cvt_pk_bf16_f32 v80, v80, v81
	v_cvt_pk_bf16_f32 v81, v82, v83
	v_cvt_pk_bf16_f32 v82, v84, v85
	v_cvt_pk_bf16_f32 v83, v86, v87
	v_cvt_pk_bf16_f32 v84, v88, v89
	v_cvt_pk_bf16_f32 v85, v90, v91
	v_cvt_pk_bf16_f32 v86, v92, v93
	v_cvt_pk_bf16_f32 v87, v94, v95
	s_waitcnt lgkmcnt(7)
	v_mfma_f32_32x32x16_bf16 v[48:63], v[80:83], v[156:159], v[48:63]
	s_waitcnt lgkmcnt(6)
	v_mfma_f32_32x32x16_bf16 v[32:47], v[80:83], v[160:163], v[32:47]
	s_waitcnt lgkmcnt(5)
	v_mfma_f32_32x32x16_bf16 v[16:31], v[80:83], v[164:167], v[16:31]
	s_waitcnt lgkmcnt(4)
	v_mfma_f32_32x32x16_bf16 v[0:15], v[80:83], v[152:155], v[0:15]
	s_waitcnt lgkmcnt(3)
	v_mfma_f32_32x32x16_bf16 v[48:63], v[84:87], v[148:151], v[48:63]
	s_waitcnt lgkmcnt(2)
	v_mfma_f32_32x32x16_bf16 v[32:47], v[84:87], v[144:147], v[32:47]
	s_waitcnt lgkmcnt(1)
	v_mfma_f32_32x32x16_bf16 v[16:31], v[84:87], v[136:139], v[16:31]
	s_waitcnt lgkmcnt(0)
	v_mfma_f32_32x32x16_bf16 v[0:15], v[84:87], v[140:143], v[0:15]
	s_andn2_b64 vcc, exec, s[8:9]
	s_cbranch_vccnz .Lat2_bot
	s_xor_b32 s7, s16, 2
	s_mul_i32 s8, s7, 0x2800
	s_add_i32 s8, s8, 32
	s_mulk_i32 s7, 0x1200
	v_add_u32_e32 v80, s7, v169
	v_add3_u32 v81, s8, v189, v190
	s_addk_i32 s8, 0x2800
	s_waitcnt vmcnt(5)
	ds_write_b128 v80, v[96:99]
	s_waitcnt vmcnt(4)
	ds_write_b128 v81, v[100:103] offset:18432
	s_waitcnt vmcnt(3)
	ds_write_b128 v81, v[120:123] offset:23552
	s_waitcnt vmcnt(2)
	ds_write_b128 v80, v[124:127] offset:4608
	v_add3_u32 v80, s8, v189, v190
	s_waitcnt vmcnt(1)
	ds_write_b128 v80, v[128:131] offset:18432
	s_waitcnt vmcnt(0)
	ds_write_b128 v80, v[132:135] offset:23552
